# x3 Toeplitz loop hand-scheduled (register sliding window for A fragments, 8-deep u prefetch) + XCD-aware block->task remap in x1/x3 so groups sharing 128B lines land on one XCD
# speedup vs baseline: 1.0392x; 1.0392x over previous
.LBB0_150:
	s_and_b32 s6, s10, 7
	s_lshl_b32 s6, s6, 2
	s_lshr_b32 s7, s10, 6
	s_add_i32 s6, s6, s7
	s_lshl_b32 s6, s6, 3
	s_bfe_u32 s7, s10, 0x30003
	s_or_b32 s6, s6, s7
	v_lshl_add_u32 v0, s6, 3, v153
	v_ashrrev_i32_e32 v2, 4, v0
	s_load_dwordx2 s[6:7], s[74:75], 0x68
	v_ashrrev_i32_e32 v3, 31, v2
	v_and_b32_e32 v8, -16, v0
	v_lshlrev_b64 v[4:5], 15, v[2:3]
	v_lshl_add_u64 v[14:15], s[2:3], 0, v[4:5]
	v_add_u32_e32 v4, v155, v8
	v_ashrrev_i32_e32 v5, 31, v4
	s_waitcnt lgkmcnt(0)
	v_lshl_add_u64 v[4:5], v[4:5], 2, s[6:7]
	v_lshl_add_u64 v[10:11], v[110:111], 1, v[14:15]
	global_load_dwordx4 v[4:7], v[4:5], off
	s_barrier
	global_load_dwordx4 v[10:13], v[10:11], off
	s_waitcnt vmcnt(0)
	ds_write_b128 v158, v[10:13]
	v_lshl_add_u64 v[10:11], v[112:113], 1, v[14:15]
	global_load_dwordx4 v[10:13], v[10:11], off
	s_waitcnt vmcnt(0)
	ds_write_b128 v159, v[10:13]
	v_lshl_add_u64 v[10:11], v[114:115], 1, v[14:15]
	global_load_dwordx4 v[10:13], v[10:11], off
	s_waitcnt vmcnt(0)
	ds_write_b128 v160, v[10:13]
	v_lshl_add_u64 v[10:11], v[116:117], 1, v[14:15]
	global_load_dwordx4 v[10:13], v[10:11], off
	s_waitcnt vmcnt(0)
	ds_write_b128 v161, v[10:13]
	s_and_saveexec_b64 s[6:7], s[38:39]
	s_cbranch_execz .LBB0_152
	v_mov_b32_e32 v10, v1
	s_nop 0
	v_mov_b32_e32 v11, v10
	v_mov_b32_e32 v12, v10
	v_mov_b32_e32 v13, v10
	ds_write_b128 v156, v[10:13]

.LBB0_156:
	s_lshl_b32 s6, s11, 8
	v_add_u32_e32 v2, s6, v163
	v_add_u32_e32 v8, s6, v165
	v_ashrrev_i32_e32 v3, 31, v2
	v_ashrrev_i32_e32 v9, 31, v8
	v_lshlrev_b64 v[2:3], 8, v[2:3]
	v_lshlrev_b64 v[8:9], 8, v[8:9]
	v_lshl_add_u64 v[2:3], v[124:125], 0, v[2:3]
	v_lshl_add_u64 v[12:13], v[124:125], 0, v[8:9]
	global_load_dwordx4 v[8:11], v[2:3], off
	s_nop 0
	global_load_dwordx4 v[12:15], v[12:13], off
	v_add_u32_e32 v2, s6, v167
	v_add_u32_e32 v16, s6, v169
	v_ashrrev_i32_e32 v3, 31, v2
	v_ashrrev_i32_e32 v17, 31, v16
	v_lshlrev_b64 v[2:3], 8, v[2:3]
	v_lshlrev_b64 v[16:17], 8, v[16:17]
	v_lshl_add_u64 v[2:3], v[124:125], 0, v[2:3]
	v_lshl_add_u64 v[20:21], v[124:125], 0, v[16:17]
	global_load_dwordx4 v[16:19], v[2:3], off
	s_nop 0
	global_load_dwordx4 v[20:23], v[20:21], off
	v_add_u32_e32 v2, s6, v171
	v_add_u32_e32 v24, s6, v173
	v_ashrrev_i32_e32 v3, 31, v2
	v_ashrrev_i32_e32 v25, 31, v24
	v_lshlrev_b64 v[2:3], 8, v[2:3]
	v_lshlrev_b64 v[24:25], 8, v[24:25]
	v_lshl_add_u64 v[2:3], v[124:125], 0, v[2:3]
	v_lshl_add_u64 v[28:29], v[124:125], 0, v[24:25]
	global_load_dwordx4 v[24:27], v[2:3], off
	s_nop 0
	global_load_dwordx4 v[28:31], v[28:29], off
	v_add_u32_e32 v2, s6, v175
	v_add_u32_e32 v32, s6, v177
	v_ashrrev_i32_e32 v3, 31, v2
	v_ashrrev_i32_e32 v33, 31, v32
	v_lshlrev_b64 v[2:3], 8, v[2:3]
	v_lshlrev_b64 v[32:33], 8, v[32:33]
	v_lshl_add_u64 v[2:3], v[124:125], 0, v[2:3]
	v_lshl_add_u64 v[36:37], v[124:125], 0, v[32:33]
	global_load_dwordx4 v[32:35], v[2:3], off
	s_nop 0
	global_load_dwordx4 v[36:39], v[36:37], off
	v_mov_b32_e32 v2, v1
	v_mov_b32_e32 v3, v1
	s_lshl_b32 s6, s11, 3
	s_lshl_b32 s12, s11, 4
	v_mov_b32_e32 v0, v1
	v_mov_b64_e32 v[74:75], v[2:3]
	v_mov_b64_e32 v[70:71], v[2:3]
	v_mov_b64_e32 v[66:67], v[2:3]
	v_mov_b64_e32 v[62:63], v[2:3]
	v_mov_b64_e32 v[58:59], v[2:3]
	v_mov_b64_e32 v[54:55], v[2:3]
	v_mov_b64_e32 v[50:51], v[2:3]
	v_mov_b64_e32 v[42:43], v[2:3]
	s_add_i32 s13, s6, 8
	s_or_b32 s14, s6, 7
	s_mov_b32 s20, 4
	s_or_b32 s15, s12, 1
	s_or_b32 s16, s12, 2
	s_or_b32 s17, s12, 3
	s_or_b32 s18, s12, 4
	s_or_b32 s19, s12, 5
	s_mov_b32 s21, 6
	s_or_b32 s22, s12, 6
	s_or_b32 s23, s12, 7
	s_or_b32 s24, s12, 8
	s_or_b32 s25, s12, 9
	s_or_b32 s26, s12, 10
	s_or_b32 s27, s12, 11
	s_or_b32 s28, s12, 12
	s_or_b32 s29, s12, 13
	s_or_b32 s30, s12, 14
	s_or_b32 s31, s12, 15
	v_mov_b32_e32 v121, v119
	v_mov_b64_e32 v[72:73], v[0:1]
	v_mov_b64_e32 v[68:69], v[0:1]
	v_mov_b64_e32 v[64:65], v[0:1]
	v_mov_b64_e32 v[60:61], v[0:1]
	v_mov_b64_e32 v[56:57], v[0:1]
	v_mov_b64_e32 v[52:53], v[0:1]
	v_mov_b64_e32 v[48:49], v[0:1]
	v_mov_b64_e32 v[40:41], v[0:1]
	s_waitcnt vmcnt(7)
	ds_write_b128 v164, v[8:11]
	s_waitcnt vmcnt(6)
	ds_write_b128 v166, v[12:15]
	s_waitcnt vmcnt(5)
	ds_write_b128 v168, v[16:19]
	s_waitcnt vmcnt(4)
	ds_write_b128 v170, v[20:23]
	s_waitcnt vmcnt(3)
	ds_write_b128 v172, v[24:27]
	s_waitcnt vmcnt(2)
	ds_write_b128 v174, v[28:31]
	s_waitcnt vmcnt(1)
	ds_write_b128 v176, v[32:35]
	s_waitcnt vmcnt(0)
	ds_write_b128 v178, v[36:39]
	s_waitcnt lgkmcnt(0)
	s_barrier
	v_mov_b32_e32 v72, 0
	v_mov_b32_e32 v73, 0
	v_mov_b32_e32 v74, 0
	v_mov_b32_e32 v75, 0
	v_mov_b32_e32 v68, 0
	v_mov_b32_e32 v69, 0
	v_mov_b32_e32 v70, 0
	v_mov_b32_e32 v71, 0
	v_mov_b32_e32 v64, 0
	v_mov_b32_e32 v65, 0
	v_mov_b32_e32 v66, 0
	v_mov_b32_e32 v67, 0
	v_mov_b32_e32 v60, 0
	v_mov_b32_e32 v61, 0
	v_mov_b32_e32 v62, 0
	v_mov_b32_e32 v63, 0
	v_mov_b32_e32 v56, 0
	v_mov_b32_e32 v57, 0
	v_mov_b32_e32 v58, 0
	v_mov_b32_e32 v59, 0
	v_mov_b32_e32 v52, 0
	v_mov_b32_e32 v53, 0
	v_mov_b32_e32 v54, 0
	v_mov_b32_e32 v55, 0
	v_mov_b32_e32 v48, 0
	v_mov_b32_e32 v49, 0
	v_mov_b32_e32 v50, 0
	v_mov_b32_e32 v51, 0
	v_mov_b32_e32 v40, 0
	v_mov_b32_e32 v41, 0
	v_mov_b32_e32 v42, 0
	v_mov_b32_e32 v43, 0
	v_mov_b32_e32 v36, 0
	v_mov_b32_e32 v37, 0
	v_mov_b32_e32 v38, 0
	v_mov_b32_e32 v39, 0
	v_mov_b32_e32 v32, 0
	v_mov_b32_e32 v33, 0
	v_mov_b32_e32 v34, 0
	v_mov_b32_e32 v35, 0
	v_mov_b32_e32 v28, 0
	v_mov_b32_e32 v29, 0
	v_mov_b32_e32 v30, 0
	v_mov_b32_e32 v31, 0
	v_mov_b32_e32 v24, 0
	v_mov_b32_e32 v25, 0
	v_mov_b32_e32 v26, 0
	v_mov_b32_e32 v27, 0
	v_mov_b32_e32 v20, 0
	v_mov_b32_e32 v21, 0
	v_mov_b32_e32 v22, 0
	v_mov_b32_e32 v23, 0
	v_mov_b32_e32 v16, 0
	v_mov_b32_e32 v17, 0
	v_mov_b32_e32 v18, 0
	v_mov_b32_e32 v19, 0
	v_mov_b32_e32 v12, 0
	v_mov_b32_e32 v13, 0
	v_mov_b32_e32 v14, 0
	v_mov_b32_e32 v15, 0
	v_mov_b32_e32 v8, 0
	v_mov_b32_e32 v9, 0
	v_mov_b32_e32 v10, 0
	v_mov_b32_e32 v11, 0
	ds_read_b128 v[204:207], v121 offset:3072
	ds_read_b128 v[208:211], v121 offset:3584
	ds_read_b128 v[212:215], v121 offset:4096
	ds_read_b128 v[216:219], v121 offset:4608
	ds_read_b128 v[220:223], v121 offset:5120
	ds_read_b128 v[224:227], v121 offset:5632
	ds_read_b128 v[228:231], v121 offset:6144
	ds_read_b128 v[232:235], v121 offset:6656
	ds_read_b128 v[236:239], v121 offset:7168
	ds_read_b128 v[240:243], v121 offset:7680
	ds_read_b128 v[244:247], v121 offset:8192
	ds_read_b128 v[248:251], v121 offset:8704
	ds_read_b128 v[76:79], v121 offset:9216
	ds_read_b128 v[80:83], v121 offset:9728
	ds_read_b128 v[84:87], v121 offset:10240
	ds_read_b128 v[88:91], v121 offset:10752
	v_mov_b32_e32 v0, v157
	v_lshl_add_u64 v[2:3], v[126:127], 0, v[0:1]
	global_load_dwordx4 v[92:95], v[2:3], off
	v_or_b32_e32 v0, 0x4000, v157
	v_lshl_add_u64 v[2:3], v[126:127], 0, v[0:1]
	global_load_dwordx4 v[96:99], v[2:3], off
	v_or_b32_e32 v0, 0x8000, v157
	v_lshl_add_u64 v[2:3], v[126:127], 0, v[0:1]
	global_load_dwordx4 v[100:103], v[2:3], off
	v_or_b32_e32 v0, 0xc000, v157
	v_lshl_add_u64 v[2:3], v[126:127], 0, v[0:1]
	global_load_dwordx4 v[44:47], v[2:3], off
	v_or_b32_e32 v0, 0x10000, v157
	v_lshl_add_u64 v[2:3], v[126:127], 0, v[0:1]
	global_load_dwordx4 v[136:139], v[2:3], off
	v_or_b32_e32 v0, 0x14000, v157
	v_lshl_add_u64 v[2:3], v[126:127], 0, v[0:1]
	global_load_dwordx4 v[140:143], v[2:3], off
	v_or_b32_e32 v0, 0x18000, v157
	v_lshl_add_u64 v[2:3], v[126:127], 0, v[0:1]
	global_load_dwordx4 v[196:199], v[2:3], off
	v_add_u32_e32 v193, 0xffffec00, v121
	s_mov_b32 s20, 0
	s_cmp_eq_u32 s11, 0
	s_cbranch_scc1 .Lmy_x3_tri
	s_waitcnt lgkmcnt(0)
.Lmy_x3_full:
	s_add_i32 s6, s20, 7
	v_lshl_or_b32 v0, s6, 14, v157
	v_lshl_add_u64 v[2:3], v[126:127], 0, v[0:1]
	global_load_dwordx4 v[200:203], v[2:3], off
	s_waitcnt vmcnt(7)
	v_mfma_f32_16x16x32_bf16 v[12:15], v[84:87], v[92:95], v[12:15]
	v_mfma_f32_16x16x32_bf16 v[8:11], v[88:91], v[92:95], v[8:11]
	ds_read_b128 v[84:87], v193 offset:7168
	ds_read_b128 v[88:91], v193 offset:7680
	v_mfma_f32_16x16x32_bf16 v[64:67], v[212:215], v[92:95], v[64:67]
	v_mfma_f32_16x16x32_bf16 v[60:63], v[216:219], v[92:95], v[60:63]
	v_mfma_f32_16x16x32_bf16 v[56:59], v[220:223], v[92:95], v[56:59]
	v_mfma_f32_16x16x32_bf16 v[52:55], v[224:227], v[92:95], v[52:55]
	v_mfma_f32_16x16x32_bf16 v[48:51], v[228:231], v[92:95], v[48:51]
	v_mfma_f32_16x16x32_bf16 v[40:43], v[232:235], v[92:95], v[40:43]
	v_mfma_f32_16x16x32_bf16 v[36:39], v[236:239], v[92:95], v[36:39]
	v_mfma_f32_16x16x32_bf16 v[32:35], v[240:243], v[92:95], v[32:35]
	v_mfma_f32_16x16x32_bf16 v[28:31], v[244:247], v[92:95], v[28:31]
	v_mfma_f32_16x16x32_bf16 v[24:27], v[248:251], v[92:95], v[24:27]
	v_mfma_f32_16x16x32_bf16 v[20:23], v[76:79], v[92:95], v[20:23]
	v_mfma_f32_16x16x32_bf16 v[16:19], v[80:83], v[92:95], v[16:19]
	s_waitcnt lgkmcnt(2)
	v_mfma_f32_16x16x32_bf16 v[72:75], v[204:207], v[92:95], v[72:75]
	v_mfma_f32_16x16x32_bf16 v[68:71], v[208:211], v[92:95], v[68:71]
	s_add_i32 s6, s20, 8
	v_lshl_or_b32 v0, s6, 14, v157
	v_lshl_add_u64 v[2:3], v[126:127], 0, v[0:1]
	global_load_dwordx4 v[92:95], v[2:3], off
	s_waitcnt vmcnt(7)
	v_mfma_f32_16x16x32_bf16 v[12:15], v[76:79], v[96:99], v[12:15]
	v_mfma_f32_16x16x32_bf16 v[8:11], v[80:83], v[96:99], v[8:11]
	ds_read_b128 v[76:79], v193 offset:6144
	ds_read_b128 v[80:83], v193 offset:6656
	v_mfma_f32_16x16x32_bf16 v[64:67], v[204:207], v[96:99], v[64:67]
	v_mfma_f32_16x16x32_bf16 v[60:63], v[208:211], v[96:99], v[60:63]
	v_mfma_f32_16x16x32_bf16 v[56:59], v[212:215], v[96:99], v[56:59]
	v_mfma_f32_16x16x32_bf16 v[52:55], v[216:219], v[96:99], v[52:55]
	v_mfma_f32_16x16x32_bf16 v[48:51], v[220:223], v[96:99], v[48:51]
	v_mfma_f32_16x16x32_bf16 v[40:43], v[224:227], v[96:99], v[40:43]
	v_mfma_f32_16x16x32_bf16 v[36:39], v[228:231], v[96:99], v[36:39]
	v_mfma_f32_16x16x32_bf16 v[32:35], v[232:235], v[96:99], v[32:35]
	v_mfma_f32_16x16x32_bf16 v[28:31], v[236:239], v[96:99], v[28:31]
	v_mfma_f32_16x16x32_bf16 v[24:27], v[240:243], v[96:99], v[24:27]
	v_mfma_f32_16x16x32_bf16 v[20:23], v[244:247], v[96:99], v[20:23]
	v_mfma_f32_16x16x32_bf16 v[16:19], v[248:251], v[96:99], v[16:19]
	s_waitcnt lgkmcnt(2)
	v_mfma_f32_16x16x32_bf16 v[72:75], v[84:87], v[96:99], v[72:75]
	v_mfma_f32_16x16x32_bf16 v[68:71], v[88:91], v[96:99], v[68:71]
	s_add_i32 s6, s20, 9
	v_lshl_or_b32 v0, s6, 14, v157
	v_lshl_add_u64 v[2:3], v[126:127], 0, v[0:1]
	global_load_dwordx4 v[96:99], v[2:3], off
	s_waitcnt vmcnt(7)
	v_mfma_f32_16x16x32_bf16 v[12:15], v[244:247], v[100:103], v[12:15]
	v_mfma_f32_16x16x32_bf16 v[8:11], v[248:251], v[100:103], v[8:11]
	ds_read_b128 v[244:247], v193 offset:5120
	ds_read_b128 v[248:251], v193 offset:5632
	v_mfma_f32_16x16x32_bf16 v[64:67], v[84:87], v[100:103], v[64:67]
	v_mfma_f32_16x16x32_bf16 v[60:63], v[88:91], v[100:103], v[60:63]
	v_mfma_f32_16x16x32_bf16 v[56:59], v[204:207], v[100:103], v[56:59]
	v_mfma_f32_16x16x32_bf16 v[52:55], v[208:211], v[100:103], v[52:55]
	v_mfma_f32_16x16x32_bf16 v[48:51], v[212:215], v[100:103], v[48:51]
	v_mfma_f32_16x16x32_bf16 v[40:43], v[216:219], v[100:103], v[40:43]
	v_mfma_f32_16x16x32_bf16 v[36:39], v[220:223], v[100:103], v[36:39]
	v_mfma_f32_16x16x32_bf16 v[32:35], v[224:227], v[100:103], v[32:35]
	v_mfma_f32_16x16x32_bf16 v[28:31], v[228:231], v[100:103], v[28:31]
	v_mfma_f32_16x16x32_bf16 v[24:27], v[232:235], v[100:103], v[24:27]
	v_mfma_f32_16x16x32_bf16 v[20:23], v[236:239], v[100:103], v[20:23]
	v_mfma_f32_16x16x32_bf16 v[16:19], v[240:243], v[100:103], v[16:19]
	s_waitcnt lgkmcnt(2)
	v_mfma_f32_16x16x32_bf16 v[72:75], v[76:79], v[100:103], v[72:75]
	v_mfma_f32_16x16x32_bf16 v[68:71], v[80:83], v[100:103], v[68:71]
	s_add_i32 s6, s20, 10
	v_lshl_or_b32 v0, s6, 14, v157
	v_lshl_add_u64 v[2:3], v[126:127], 0, v[0:1]
	global_load_dwordx4 v[100:103], v[2:3], off
	s_waitcnt vmcnt(7)
	v_mfma_f32_16x16x32_bf16 v[12:15], v[236:239], v[44:47], v[12:15]
	v_mfma_f32_16x16x32_bf16 v[8:11], v[240:243], v[44:47], v[8:11]
	ds_read_b128 v[236:239], v193 offset:4096
	ds_read_b128 v[240:243], v193 offset:4608
	v_mfma_f32_16x16x32_bf16 v[64:67], v[76:79], v[44:47], v[64:67]
	v_mfma_f32_16x16x32_bf16 v[60:63], v[80:83], v[44:47], v[60:63]
	v_mfma_f32_16x16x32_bf16 v[56:59], v[84:87], v[44:47], v[56:59]
	v_mfma_f32_16x16x32_bf16 v[52:55], v[88:91], v[44:47], v[52:55]
	v_mfma_f32_16x16x32_bf16 v[48:51], v[204:207], v[44:47], v[48:51]
	v_mfma_f32_16x16x32_bf16 v[40:43], v[208:211], v[44:47], v[40:43]
	v_mfma_f32_16x16x32_bf16 v[36:39], v[212:215], v[44:47], v[36:39]
	v_mfma_f32_16x16x32_bf16 v[32:35], v[216:219], v[44:47], v[32:35]
	v_mfma_f32_16x16x32_bf16 v[28:31], v[220:223], v[44:47], v[28:31]
	v_mfma_f32_16x16x32_bf16 v[24:27], v[224:227], v[44:47], v[24:27]
	v_mfma_f32_16x16x32_bf16 v[20:23], v[228:231], v[44:47], v[20:23]
	v_mfma_f32_16x16x32_bf16 v[16:19], v[232:235], v[44:47], v[16:19]
	s_waitcnt lgkmcnt(2)
	v_mfma_f32_16x16x32_bf16 v[72:75], v[244:247], v[44:47], v[72:75]
	v_mfma_f32_16x16x32_bf16 v[68:71], v[248:251], v[44:47], v[68:71]
	s_add_i32 s6, s20, 11
	v_lshl_or_b32 v0, s6, 14, v157
	v_lshl_add_u64 v[2:3], v[126:127], 0, v[0:1]
	global_load_dwordx4 v[44:47], v[2:3], off
	s_waitcnt vmcnt(7)
	v_mfma_f32_16x16x32_bf16 v[12:15], v[228:231], v[136:139], v[12:15]
	v_mfma_f32_16x16x32_bf16 v[8:11], v[232:235], v[136:139], v[8:11]
	ds_read_b128 v[228:231], v193 offset:3072
	ds_read_b128 v[232:235], v193 offset:3584
	v_mfma_f32_16x16x32_bf16 v[64:67], v[244:247], v[136:139], v[64:67]
	v_mfma_f32_16x16x32_bf16 v[60:63], v[248:251], v[136:139], v[60:63]
	v_mfma_f32_16x16x32_bf16 v[56:59], v[76:79], v[136:139], v[56:59]
	v_mfma_f32_16x16x32_bf16 v[52:55], v[80:83], v[136:139], v[52:55]
	v_mfma_f32_16x16x32_bf16 v[48:51], v[84:87], v[136:139], v[48:51]
	v_mfma_f32_16x16x32_bf16 v[40:43], v[88:91], v[136:139], v[40:43]
	v_mfma_f32_16x16x32_bf16 v[36:39], v[204:207], v[136:139], v[36:39]
	v_mfma_f32_16x16x32_bf16 v[32:35], v[208:211], v[136:139], v[32:35]
	v_mfma_f32_16x16x32_bf16 v[28:31], v[212:215], v[136:139], v[28:31]
	v_mfma_f32_16x16x32_bf16 v[24:27], v[216:219], v[136:139], v[24:27]
	v_mfma_f32_16x16x32_bf16 v[20:23], v[220:223], v[136:139], v[20:23]
	v_mfma_f32_16x16x32_bf16 v[16:19], v[224:227], v[136:139], v[16:19]
	s_waitcnt lgkmcnt(2)
	v_mfma_f32_16x16x32_bf16 v[72:75], v[236:239], v[136:139], v[72:75]
	v_mfma_f32_16x16x32_bf16 v[68:71], v[240:243], v[136:139], v[68:71]
	s_add_i32 s6, s20, 12
	v_lshl_or_b32 v0, s6, 14, v157
	v_lshl_add_u64 v[2:3], v[126:127], 0, v[0:1]
	global_load_dwordx4 v[136:139], v[2:3], off
	s_waitcnt vmcnt(7)
	v_mfma_f32_16x16x32_bf16 v[12:15], v[220:223], v[140:143], v[12:15]
	v_mfma_f32_16x16x32_bf16 v[8:11], v[224:227], v[140:143], v[8:11]
	ds_read_b128 v[220:223], v193 offset:2048
	ds_read_b128 v[224:227], v193 offset:2560
	v_mfma_f32_16x16x32_bf16 v[64:67], v[236:239], v[140:143], v[64:67]
	v_mfma_f32_16x16x32_bf16 v[60:63], v[240:243], v[140:143], v[60:63]
	v_mfma_f32_16x16x32_bf16 v[56:59], v[244:247], v[140:143], v[56:59]
	v_mfma_f32_16x16x32_bf16 v[52:55], v[248:251], v[140:143], v[52:55]
	v_mfma_f32_16x16x32_bf16 v[48:51], v[76:79], v[140:143], v[48:51]
	v_mfma_f32_16x16x32_bf16 v[40:43], v[80:83], v[140:143], v[40:43]
	v_mfma_f32_16x16x32_bf16 v[36:39], v[84:87], v[140:143], v[36:39]
	v_mfma_f32_16x16x32_bf16 v[32:35], v[88:91], v[140:143], v[32:35]
	v_mfma_f32_16x16x32_bf16 v[28:31], v[204:207], v[140:143], v[28:31]
	v_mfma_f32_16x16x32_bf16 v[24:27], v[208:211], v[140:143], v[24:27]
	v_mfma_f32_16x16x32_bf16 v[20:23], v[212:215], v[140:143], v[20:23]
	v_mfma_f32_16x16x32_bf16 v[16:19], v[216:219], v[140:143], v[16:19]
	s_waitcnt lgkmcnt(2)
	v_mfma_f32_16x16x32_bf16 v[72:75], v[228:231], v[140:143], v[72:75]
	v_mfma_f32_16x16x32_bf16 v[68:71], v[232:235], v[140:143], v[68:71]
	s_add_i32 s6, s20, 13
	v_lshl_or_b32 v0, s6, 14, v157
	v_lshl_add_u64 v[2:3], v[126:127], 0, v[0:1]
	global_load_dwordx4 v[140:143], v[2:3], off
	s_waitcnt vmcnt(7)
	v_mfma_f32_16x16x32_bf16 v[12:15], v[212:215], v[196:199], v[12:15]
	v_mfma_f32_16x16x32_bf16 v[8:11], v[216:219], v[196:199], v[8:11]
	ds_read_b128 v[212:215], v193 offset:1024
	ds_read_b128 v[216:219], v193 offset:1536
	v_mfma_f32_16x16x32_bf16 v[64:67], v[228:231], v[196:199], v[64:67]
	v_mfma_f32_16x16x32_bf16 v[60:63], v[232:235], v[196:199], v[60:63]
	v_mfma_f32_16x16x32_bf16 v[56:59], v[236:239], v[196:199], v[56:59]
	v_mfma_f32_16x16x32_bf16 v[52:55], v[240:243], v[196:199], v[52:55]
	v_mfma_f32_16x16x32_bf16 v[48:51], v[244:247], v[196:199], v[48:51]
	v_mfma_f32_16x16x32_bf16 v[40:43], v[248:251], v[196:199], v[40:43]
	v_mfma_f32_16x16x32_bf16 v[36:39], v[76:79], v[196:199], v[36:39]
	v_mfma_f32_16x16x32_bf16 v[32:35], v[80:83], v[196:199], v[32:35]
	v_mfma_f32_16x16x32_bf16 v[28:31], v[84:87], v[196:199], v[28:31]
	v_mfma_f32_16x16x32_bf16 v[24:27], v[88:91], v[196:199], v[24:27]
	v_mfma_f32_16x16x32_bf16 v[20:23], v[204:207], v[196:199], v[20:23]
	v_mfma_f32_16x16x32_bf16 v[16:19], v[208:211], v[196:199], v[16:19]
	s_waitcnt lgkmcnt(2)
	v_mfma_f32_16x16x32_bf16 v[72:75], v[220:223], v[196:199], v[72:75]
	v_mfma_f32_16x16x32_bf16 v[68:71], v[224:227], v[196:199], v[68:71]
	s_add_i32 s6, s20, 14
	v_lshl_or_b32 v0, s6, 14, v157
	v_lshl_add_u64 v[2:3], v[126:127], 0, v[0:1]
	global_load_dwordx4 v[196:199], v[2:3], off
	s_waitcnt vmcnt(7)
	v_mfma_f32_16x16x32_bf16 v[12:15], v[204:207], v[200:203], v[12:15]
	v_mfma_f32_16x16x32_bf16 v[8:11], v[208:211], v[200:203], v[8:11]
	ds_read_b128 v[204:207], v193 offset:0
	ds_read_b128 v[208:211], v193 offset:512
	v_mfma_f32_16x16x32_bf16 v[64:67], v[220:223], v[200:203], v[64:67]
	v_mfma_f32_16x16x32_bf16 v[60:63], v[224:227], v[200:203], v[60:63]
	v_mfma_f32_16x16x32_bf16 v[56:59], v[228:231], v[200:203], v[56:59]
	v_mfma_f32_16x16x32_bf16 v[52:55], v[232:235], v[200:203], v[52:55]
	v_mfma_f32_16x16x32_bf16 v[48:51], v[236:239], v[200:203], v[48:51]
	v_mfma_f32_16x16x32_bf16 v[40:43], v[240:243], v[200:203], v[40:43]
	v_mfma_f32_16x16x32_bf16 v[36:39], v[244:247], v[200:203], v[36:39]
	v_mfma_f32_16x16x32_bf16 v[32:35], v[248:251], v[200:203], v[32:35]
	v_mfma_f32_16x16x32_bf16 v[28:31], v[76:79], v[200:203], v[28:31]
	v_mfma_f32_16x16x32_bf16 v[24:27], v[80:83], v[200:203], v[24:27]
	v_mfma_f32_16x16x32_bf16 v[20:23], v[84:87], v[200:203], v[20:23]
	v_mfma_f32_16x16x32_bf16 v[16:19], v[88:91], v[200:203], v[16:19]
	s_waitcnt lgkmcnt(2)
	v_mfma_f32_16x16x32_bf16 v[72:75], v[212:215], v[200:203], v[72:75]
	v_mfma_f32_16x16x32_bf16 v[68:71], v[216:219], v[200:203], v[68:71]
	v_add_u32_e32 v193, 0xffffe000, v193
	s_add_i32 s20, s20, 8
	s_lshl_b32 s6, s11, 3
	s_cmp_lt_u32 s20, s6
	s_cbranch_scc1 .Lmy_x3_full
.Lmy_x3_tri:
	s_waitcnt lgkmcnt(0)
	s_add_i32 s6, s20, 7
	v_lshl_or_b32 v0, s6, 14, v157
	v_lshl_add_u64 v[2:3], v[126:127], 0, v[0:1]
	global_load_dwordx4 v[200:203], v[2:3], off
	s_waitcnt vmcnt(7)
	v_mfma_f32_16x16x32_bf16 v[72:75], v[204:207], v[92:95], v[72:75]
	v_mfma_f32_16x16x32_bf16 v[68:71], v[208:211], v[92:95], v[68:71]
	v_mfma_f32_16x16x32_bf16 v[64:67], v[212:215], v[92:95], v[64:67]
	v_mfma_f32_16x16x32_bf16 v[60:63], v[216:219], v[92:95], v[60:63]
	v_mfma_f32_16x16x32_bf16 v[56:59], v[220:223], v[92:95], v[56:59]
	v_mfma_f32_16x16x32_bf16 v[52:55], v[224:227], v[92:95], v[52:55]
	v_mfma_f32_16x16x32_bf16 v[48:51], v[228:231], v[92:95], v[48:51]
	v_mfma_f32_16x16x32_bf16 v[40:43], v[232:235], v[92:95], v[40:43]
	v_mfma_f32_16x16x32_bf16 v[36:39], v[236:239], v[92:95], v[36:39]
	v_mfma_f32_16x16x32_bf16 v[32:35], v[240:243], v[92:95], v[32:35]
	v_mfma_f32_16x16x32_bf16 v[28:31], v[244:247], v[92:95], v[28:31]
	v_mfma_f32_16x16x32_bf16 v[24:27], v[248:251], v[92:95], v[24:27]
	v_mfma_f32_16x16x32_bf16 v[20:23], v[76:79], v[92:95], v[20:23]
	v_mfma_f32_16x16x32_bf16 v[16:19], v[80:83], v[92:95], v[16:19]
	v_mfma_f32_16x16x32_bf16 v[12:15], v[84:87], v[92:95], v[12:15]
	v_mfma_f32_16x16x32_bf16 v[8:11], v[88:91], v[92:95], v[8:11]
	s_waitcnt vmcnt(6)
	v_mfma_f32_16x16x32_bf16 v[64:67], v[204:207], v[96:99], v[64:67]
	v_mfma_f32_16x16x32_bf16 v[60:63], v[208:211], v[96:99], v[60:63]
	v_mfma_f32_16x16x32_bf16 v[56:59], v[212:215], v[96:99], v[56:59]
	v_mfma_f32_16x16x32_bf16 v[52:55], v[216:219], v[96:99], v[52:55]
	v_mfma_f32_16x16x32_bf16 v[48:51], v[220:223], v[96:99], v[48:51]
	v_mfma_f32_16x16x32_bf16 v[40:43], v[224:227], v[96:99], v[40:43]
	v_mfma_f32_16x16x32_bf16 v[36:39], v[228:231], v[96:99], v[36:39]
	v_mfma_f32_16x16x32_bf16 v[32:35], v[232:235], v[96:99], v[32:35]
	v_mfma_f32_16x16x32_bf16 v[28:31], v[236:239], v[96:99], v[28:31]
	v_mfma_f32_16x16x32_bf16 v[24:27], v[240:243], v[96:99], v[24:27]
	v_mfma_f32_16x16x32_bf16 v[20:23], v[244:247], v[96:99], v[20:23]
	v_mfma_f32_16x16x32_bf16 v[16:19], v[248:251], v[96:99], v[16:19]
	v_mfma_f32_16x16x32_bf16 v[12:15], v[76:79], v[96:99], v[12:15]
	v_mfma_f32_16x16x32_bf16 v[8:11], v[80:83], v[96:99], v[8:11]
	s_waitcnt vmcnt(5)
	v_mfma_f32_16x16x32_bf16 v[56:59], v[204:207], v[100:103], v[56:59]
	v_mfma_f32_16x16x32_bf16 v[52:55], v[208:211], v[100:103], v[52:55]
	v_mfma_f32_16x16x32_bf16 v[48:51], v[212:215], v[100:103], v[48:51]
	v_mfma_f32_16x16x32_bf16 v[40:43], v[216:219], v[100:103], v[40:43]
	v_mfma_f32_16x16x32_bf16 v[36:39], v[220:223], v[100:103], v[36:39]
	v_mfma_f32_16x16x32_bf16 v[32:35], v[224:227], v[100:103], v[32:35]
	v_mfma_f32_16x16x32_bf16 v[28:31], v[228:231], v[100:103], v[28:31]
	v_mfma_f32_16x16x32_bf16 v[24:27], v[232:235], v[100:103], v[24:27]
	v_mfma_f32_16x16x32_bf16 v[20:23], v[236:239], v[100:103], v[20:23]
	v_mfma_f32_16x16x32_bf16 v[16:19], v[240:243], v[100:103], v[16:19]
	v_mfma_f32_16x16x32_bf16 v[12:15], v[244:247], v[100:103], v[12:15]
	v_mfma_f32_16x16x32_bf16 v[8:11], v[248:251], v[100:103], v[8:11]
	s_waitcnt vmcnt(4)
	v_mfma_f32_16x16x32_bf16 v[48:51], v[204:207], v[44:47], v[48:51]
	v_mfma_f32_16x16x32_bf16 v[40:43], v[208:211], v[44:47], v[40:43]
	v_mfma_f32_16x16x32_bf16 v[36:39], v[212:215], v[44:47], v[36:39]
	v_mfma_f32_16x16x32_bf16 v[32:35], v[216:219], v[44:47], v[32:35]
	v_mfma_f32_16x16x32_bf16 v[28:31], v[220:223], v[44:47], v[28:31]
	v_mfma_f32_16x16x32_bf16 v[24:27], v[224:227], v[44:47], v[24:27]
	v_mfma_f32_16x16x32_bf16 v[20:23], v[228:231], v[44:47], v[20:23]
	v_mfma_f32_16x16x32_bf16 v[16:19], v[232:235], v[44:47], v[16:19]
	v_mfma_f32_16x16x32_bf16 v[12:15], v[236:239], v[44:47], v[12:15]
	v_mfma_f32_16x16x32_bf16 v[8:11], v[240:243], v[44:47], v[8:11]
	s_waitcnt vmcnt(3)
	v_mfma_f32_16x16x32_bf16 v[36:39], v[204:207], v[136:139], v[36:39]
	v_mfma_f32_16x16x32_bf16 v[32:35], v[208:211], v[136:139], v[32:35]
	v_mfma_f32_16x16x32_bf16 v[28:31], v[212:215], v[136:139], v[28:31]
	v_mfma_f32_16x16x32_bf16 v[24:27], v[216:219], v[136:139], v[24:27]
	v_mfma_f32_16x16x32_bf16 v[20:23], v[220:223], v[136:139], v[20:23]
	v_mfma_f32_16x16x32_bf16 v[16:19], v[224:227], v[136:139], v[16:19]
	v_mfma_f32_16x16x32_bf16 v[12:15], v[228:231], v[136:139], v[12:15]
	v_mfma_f32_16x16x32_bf16 v[8:11], v[232:235], v[136:139], v[8:11]
	s_waitcnt vmcnt(2)
	v_mfma_f32_16x16x32_bf16 v[28:31], v[204:207], v[140:143], v[28:31]
	v_mfma_f32_16x16x32_bf16 v[24:27], v[208:211], v[140:143], v[24:27]
	v_mfma_f32_16x16x32_bf16 v[20:23], v[212:215], v[140:143], v[20:23]
	v_mfma_f32_16x16x32_bf16 v[16:19], v[216:219], v[140:143], v[16:19]
	v_mfma_f32_16x16x32_bf16 v[12:15], v[220:223], v[140:143], v[12:15]
	v_mfma_f32_16x16x32_bf16 v[8:11], v[224:227], v[140:143], v[8:11]
	s_waitcnt vmcnt(1)
	v_mfma_f32_16x16x32_bf16 v[20:23], v[204:207], v[196:199], v[20:23]
	v_mfma_f32_16x16x32_bf16 v[16:19], v[208:211], v[196:199], v[16:19]
	v_mfma_f32_16x16x32_bf16 v[12:15], v[212:215], v[196:199], v[12:15]
	v_mfma_f32_16x16x32_bf16 v[8:11], v[216:219], v[196:199], v[8:11]
	s_waitcnt vmcnt(0)
	v_mfma_f32_16x16x32_bf16 v[12:15], v[204:207], v[200:203], v[12:15]
	v_mfma_f32_16x16x32_bf16 v[8:11], v[208:211], v[200:203], v[8:11]
	s_branch .LBB0_153

.LBB0_300:
	s_andn2_b64 vcc, exec, s[0:1]
	s_cbranch_vccnz .LBB0_306
	s_mov_b32 s4, s61
	s_cmp_lg_u32 s66, 0x100
	s_cbranch_scc1 .Lmy_x1_noremap
	s_and_b32 s5, s4, 7
	s_lshl_b32 s5, s5, 2
	s_lshr_b32 s0, s4, 6
	s_add_i32 s5, s5, s0
	s_lshl_b32 s5, s5, 3
	s_bfe_u32 s0, s4, 0x30003
	s_or_b32 s4, s5, s0
.Lmy_x1_noremap:
	v_mov_b32_e32 v0, v1
	s_cmpk_gt_i32 s4, 0xff
	s_cbranch_scc1 .LBB0_306
	v_mbcnt_lo_u32_b32 v0, -1, v0
	v_mbcnt_hi_u32_b32 v0, -1, v0
	s_load_dwordx2 s[0:1], s[74:75], 0xf0
	v_add_u32_e32 v2, s67, v0
	v_and_b32_e32 v43, 15, v0
	v_lshrrev_b32_e32 v0, 4, v2
	v_lshlrev_b32_e32 v4, 3, v0
	v_bfe_u32 v3, v2, 4, 2
	v_and_b32_e32 v5, 8, v4
	v_lshlrev_b32_e32 v6, 7, v2
	s_movk_i32 s5, 0x1000
	v_ashrrev_i32_e32 v41, 6, v2
	v_lshlrev_b32_e32 v0, 3, v3
	v_and_b32_e32 v2, 24, v4
	v_and_or_b32 v4, v6, s5, v5
	v_lshlrev_b32_e32 v3, 4, v3
	s_waitcnt lgkmcnt(0)
	s_add_u32 s2, s0, 0x26c00000
	v_lshlrev_b32_e32 v4, 1, v4
	v_lshlrev_b32_e32 v5, 18, v43
	v_lshlrev_b32_e32 v6, 4, v41
	v_lshl_or_b32 v40, v43, 11, v3
	s_addc_u32 s3, s1, 0
	v_or_b32_e32 v38, 0x16c0c000, v4
	v_mov_b32_e32 v39, v1
	v_lshl_add_u32 v47, s4, 3, v41
	v_lshl_add_u32 v51, s4, 7, v6
	v_or_b32_e32 v42, 0xc0, v40
	v_or_b32_e32 v44, 0x16c08000, v4
	v_mov_b32_e32 v45, v1
	v_or_b32_e32 v46, 0x80, v40
	v_or_b32_e32 v48, 0x16c04000, v4
	v_mov_b32_e32 v49, v1
	v_or_b32_e32 v50, 64, v40
	v_or_b32_e32 v52, 0x16c00000, v4
	v_mov_b32_e32 v53, v1
	v_lshlrev_b32_e32 v78, 1, v5
	v_lshlrev_b32_e32 v54, 2, v0
	v_lshlrev_b32_e32 v56, 2, v2
